# attention: removed the compiler's conservative one-state pads between consecutive inline-asm plain f32 VALU ops (max3/add/fma chains), 98 sites
# speedup vs baseline: 1.0141x; 1.0141x over previous
; __device__ __forceinline__ void attn_unit(LAS unsigned char* lds, const bf16* Qh, const bf16* Kh, const bf16* VTh, const float* nrm, bf16* Y, const float* subln, float lam, int b, int h, int qb) {
;     ...
;     const size_t tokb = (size_t)b * SEQ; const int q0 = qb * 128, qw0 = q0 + wq * 32;
;     const int bh = b * 16 + h;
;     const int qso = OFF_Q + wid * 4096 + lane * 16;
;     { const bf16* qp = Qh + ((size_t)bh * 4096 + qw0 + r32) * 128 + comp * 64 + hi * 8;
; #pragma unroll
;       for (int d0 = 0; d0 < 4; ++d0) *(LAS bf16x8*)(lds + qso + d0 * 1024) = *(const bf16x8*)(qp + d0 * 16); }
;     const char* kgb = (const char*)(Kh + (size_t)bh * 4096 * 128);
;     const char* vgb = (const char*)(VTh + (size_t)bh * 4096 * 128);
;     const unsigned goff = (unsigned)tid * 16u;
;     const int kl0 = OFF_K + (tid >> 4) * KROW + (tid & 15) * 16, vl0 = OFF_V + (tid >> 3) * VROW + (tid & 7) * 16;
;     const int sig = (r32 & ~12) | ((r32 & 4) << 1) | ((r32 & 8) >> 1);
;     const int kfo = OFF_K + sig * KROW + comp * 128 + hi * 16;
;     const int vfo = OFF_V + r32 * VROW + hi * 16;
;     LAS float* wsf = (LAS float*)(lds + OFF_WS) + wid * 64;
;     LAS float* tminb = (LAS float*)(lds + OFF_TMIN);
;     const float slope2 = exp2f(-0.5f * (float)(h + 1)) * LOG2E;
;     const int qpos = qw0 + r32;
;     const int u0 = 2 * qb, u1 = 2 * qb + 1, u2 = (qb == 0) ? 2 : (qb == 31 ? 61 : 2 * qb - 1), u3 = (qb == 0) ? 3 : (qb == 31 ? 60 : 2 * qb + 2);
;     int ktv = (lane == 0) ? u0 : (lane == 1) ? u1 : (lane == 2) ? u2 : u3;
;     const float* nb = nrm + (size_t)b * 64 * 64;
;     const float k2a = nb[lane * 64 + 32 + 2 * h], k2b = nb[lane * 64 + 32 + 2 * h + 1];
;     const float q2a = fmaxf(nb[u0 * 64 + 2 * h], nb[u1 * 64 + 2 * h]), q2b = fmaxf(nb[u0 * 64 + 2 * h + 1], nb[u1 * 64 + 2 * h + 1]);
;     f32x16 o[4];
; #pragma unroll
;     for (int i = 0; i < 4; ++i) o[i] = f32x16{};
;     float mhat = 0.f, lsum = 0.f, tmax = -INFINITY; bool resc = false;
;     v4u pw[4] = {};
;     v4u kreg[2], vreg[2];
;     ...
;     ATT_LOAD(u0); ATT_STORE(0); ATT_LOAD(u1);
;     ATT_BAR();
;     int T = 4; unsigned long long rest = 0ull;
; __global__ void __launch_bounds__(NWAVES * 64, 2) mega_fwd(Args args) {
;     ...
;             const int unit = *uq;
;             if (unit < 0) break;
;             const int y = unit >> 8, e = unit & 255, h = (e >> 7) ? y : 15 - y, b = (e >> 5) & 3, qb = e & 31;
.LBB0_911:
	s_or_b64 exec, exec, s[10:11]
	v_mov_b32_e32 v0, s94
	s_waitcnt lgkmcnt(0)
	s_barrier
	ds_read_b32 v0, v0
	s_waitcnt lgkmcnt(0)
	v_cmp_gt_i32_e32 vcc, 0, v0
	v_readfirstlane_b32 s0, v0
	s_cbranch_vccnz .LBB0_921
	s_lshr_b32 s1, s0, 8
	s_and_b32 s3, s0, 0x80
	s_sub_i32 s5, 15, s1
	v_mov_b32_e32 v6, v248
	s_cmp_eq_u32 s3, 0
	s_cselect_b32 s5, s5, s1
	v_readfirstlane_b32 s81, v6
	s_ashr_i32 s1, s81, 6
	s_and_b32 s3, s0, 31
	s_and_b32 s14, s1, 3
	s_bfe_u32 s80, s0, 0x20005
	s_lshl_b32 s0, s3, 7
	s_lshl_b32 s6, s14, 5
	s_or_b32 s18, s6, s0
	s_lshl_b32 s6, s80, 4
	s_add_i32 s6, s6, s5
	s_ashr_i32 s7, s6, 31
	s_lshl_b64 s[10:11], s[6:7], 12
	v_and_b32_e32 v202, 31, v6
	s_or_b32 s10, s10, s18
	s_ashr_i32 s15, s81, 8
	v_or_b32_e32 v0, s10, v202
	v_mov_b32_e32 v1, s11
	v_lshlrev_b64 v[0:1], 8, v[0:1]
	s_lshl_b32 s10, s15, 6
	v_bfe_u32 v201, v6, 5, 1
	v_lshl_add_u64 v[0:1], s[26:27], 0, v[0:1]
	s_ashr_i32 s11, s10, 31
	v_and_b32_e32 v203, 63, v6
	v_lshl_add_u64 v[0:1], s[10:11], 1, v[0:1]
	v_lshlrev_b32_e32 v180, 4, v201
	v_mov_b32_e32 v181, v177
	v_lshl_add_u64 v[4:5], v[0:1], 0, v[180:181]
	v_lshl_add_u32 v0, v203, 4, 0
	s_lshl_b32 s12, s1, 12
	v_add_u32_e32 v0, 0x1ac80, v0
	v_add_u32_e32 v210, s12, v0
	global_load_dwordx4 v[0:3], v[4:5], off
	s_lshl_b64 s[12:13], s[6:7], 20
	s_movk_i32 s6, 0x110
	s_add_u32 s68, s38, s12
	s_addc_u32 s69, s39, s13
	s_lshl_b32 s64, s15, 7
	v_lshlrev_b32_e32 v176, 6, v203
	v_lshlrev_b32_e32 v216, 4, v6
	v_lshl_add_u32 v8, s3, 15, v216
	v_add_u32_e32 v12, 0x2000, v8
	v_and_b32_e32 v32, 0xf0, v216
	v_and_b32_e32 v34, 0x70, v216
	v_lshlrev_b32_e32 v209, 3, v201
	v_or_b32_e32 v212, s18, v202
	s_waitcnt vmcnt(0)
	ds_write_b128 v210, v[0:3]
	global_load_dwordx4 v[0:3], v[4:5], off offset:32
	s_waitcnt vmcnt(0)
	ds_write_b128 v210, v[0:3] offset:1024
	global_load_dwordx4 v[0:3], v[4:5], off offset:64
	s_waitcnt vmcnt(0)
	ds_write_b128 v210, v[0:3] offset:2048
	global_load_dwordx4 v[0:3], v[4:5], off offset:96
	s_waitcnt vmcnt(0)
	ds_write_b128 v210, v[0:3] offset:3072
	v_lshrrev_b32_e32 v0, 4, v6
	v_mul_lo_u32 v30, v0, s6
	v_lshrrev_b32_e32 v0, 3, v6
	v_lshlrev_b32_e32 v1, 1, v6
	v_lshrrev_b32_e32 v2, 1, v6
	v_mul_lo_u32 v31, v0, s83
	v_and_b32_e32 v0, 19, v6
	v_and_b32_e32 v1, 8, v1
	v_and_b32_e32 v2, 4, v2
	s_add_i32 s6, s5, 1
	v_or3_b32 v2, v0, v1, v2
	v_cvt_f32_i32_e32 v0, s6
	s_mov_b32 s6, 0xc2fc0000
	v_mul_u32_u24_e32 v33, 0x110, v2
	v_add3_u32 v16, 0, v30, v32
	v_mul_f32_e32 v1, -0.5, v0
	v_cmp_gt_f32_e32 vcc, s6, v1
	s_and_b64 s[6:7], vcc, exec
	s_cselect_b32 s6, 0xffffffc0, 0
	v_cndmask_b32_e32 v1, 0, v249, vcc
	v_fmac_f32_e32 v1, -0.5, v0
	v_exp_f32_e32 v0, v1
	v_cmp_eq_u32_e32 vcc, 1, v203
	v_ldexp_f32 v0, v0, s6
	s_lshl_b32 s6, s3, 1
	s_or_b32 s24, s6, 1
	s_add_i32 s7, s6, -1
	s_add_i32 s10, s6, 2
	s_cmp_lg_u32 s3, 31
	s_cselect_b32 s10, s10, 60
	s_cmp_eq_u32 s3, 0
	s_cselect_b32 s33, 2, s7
	s_cselect_b32 s25, 3, s10
	v_mul_f32_e32 v208, 0x3fb8aa3b, v0
	v_cmp_eq_u32_e64 s[10:11], 2, v203
	v_mov_b32_e32 v0, s25
	v_mov_b32_e32 v1, s33
	s_lshl_b32 s7, s80, 14
	v_cndmask_b32_e64 v0, v0, v1, s[10:11]
	s_add_u32 s10, s35, s7
	s_addc_u32 s11, s92, 0
	s_lshl_b32 s16, s5, 1
	s_add_i32 s66, s16, s0
	s_ashr_i32 s67, s66, 31
	s_ashr_i32 s17, s16, 31
	s_lshl_b64 s[66:67], s[66:67], 2
	s_add_u32 s66, s10, s66
	v_mov_b32_e32 v1, s24
	s_addc_u32 s67, s11, s67
	s_lshl_b32 s7, s24, 6
	v_cndmask_b32_e32 v3, v0, v1, vcc
	v_lshl_add_u64 v[0:1], s[16:17], 0, v[176:177]
	s_add_i32 s16, s7, s16
	s_ashr_i32 s17, s16, 31
	s_lshl_b64 s[16:17], s[16:17], 2
	v_lshl_add_u64 v[0:1], v[0:1], 2, s[10:11]
	s_add_u32 s10, s10, s16
	s_addc_u32 s11, s11, s17
	s_add_u32 s70, s42, s12
	global_load_dwordx2 v[24:25], v[0:1], off offset:128
	global_load_dwordx2 v[26:27], v177, s[66:67]
	s_addc_u32 s71, s43, s13
	v_cmp_eq_u32_e64 s[12:13], 0, v203
	v_mov_b32_e32 v0, s6
	global_load_dwordx2 v[28:29], v177, s[10:11]
	v_cndmask_b32_e64 v213, v3, v0, s[12:13]
	global_load_dwordx4 v[0:3], v8, s[70:71]
	global_load_dwordx4 v[4:7], v12, s[70:71]
	s_nop 0
	global_load_dwordx4 v[8:11], v8, s[68:69]
	s_nop 0
	global_load_dwordx4 v[12:15], v12, s[68:69]
	v_readlane_b32 s3, v213, 2
	s_add_i32 s7, s64, 0
	v_add3_u32 v217, s7, v33, v180
	s_waitcnt vmcnt(3)
	ds_write_b128 v16, v[0:3]
	s_waitcnt vmcnt(2)
	ds_write_b128 v16, v[4:7] offset:8704
	v_add3_u32 v0, 0, v31, v34
	s_waitcnt vmcnt(1)
	ds_write_b128 v0, v[8:11] offset:52224
	s_waitcnt vmcnt(0)
	ds_write_b128 v0, v[12:15] offset:61440
	v_lshl_add_u32 v8, s24, 14, v216
	v_add_u32_e32 v12, 0x2000, v8
	v_add_u32_e32 v17, 0xcc00, v0
	global_load_dwordx4 v[0:3], v8, s[70:71]
	global_load_dwordx4 v[4:7], v12, s[70:71]
	s_nop 0
	global_load_dwordx4 v[8:11], v8, s[68:69]
	s_nop 0
	global_load_dwordx4 v[12:15], v12, s[68:69]
	s_waitcnt lgkmcnt(0)
	s_barrier
	s_waitcnt vmcnt(3)
	ds_write_b128 v16, v[0:3] offset:17408
	s_waitcnt vmcnt(2)
	ds_write_b128 v16, v[4:7] offset:26112
	s_waitcnt vmcnt(1)
	ds_write_b128 v17, v[8:11] offset:18432
	s_waitcnt vmcnt(0)
	ds_write_b128 v17, v[12:15] offset:27648
	v_lshl_add_u32 v0, s3, 14, v216
	v_add_u32_e32 v1, 0x2000, v0
	global_load_dwordx4 v[128:131], v0, s[70:71]
	global_load_dwordx4 v[132:135], v1, s[70:71]
	global_load_dwordx4 v[136:139], v0, s[68:69]
	global_load_dwordx4 v[140:143], v1, s[68:69]
	v_readlane_b32 s3, v213, 0
	s_lshl_b32 s3, s3, 6
	s_or_b32 s7, s3, 63
	v_or_b32_e32 v0, s3, v209
	v_sub_u32_e32 v16, v212, v0
	ds_read_b128 v[12:15], v210
	ds_read_b128 v[8:11], v210 offset:1024
	ds_read_b128 v[4:7], v210 offset:2048
	ds_read_b128 v[0:3], v210 offset:3072
	s_cmp_lt_i32 s7, s18
	v_cvt_f32_i32_e32 v35, v16
	ds_read_b128 v[20:23], v217
	ds_read_b128 v[16:19], v217 offset:8704
	s_cselect_b64 s[10:11], -1, 0
	s_or_b32 s7, s18, 31
	s_cmp_gt_i32 s3, s7
	s_cselect_b64 s[16:17], -1, 0
	s_or_b64 s[66:67], s[10:11], s[16:17]
	s_mov_b64 s[16:17], -1
	s_andn2_b64 vcc, exec, s[66:67]
	s_cbranch_vccz .LBB0_914
	v_add_f32_e32 v36, v35, v179
	v_xor_b32_e32 v39, 0x80000000, v208
	v_add_f32_e32 v37, v36, v179
	v_fma_f32 v72, |v36|, v39, v184
	v_add_f32_e32 v40, v35, v185
	v_add_f32_e32 v36, v36, v185
	v_fma_f32 v64, |v35|, v39, v184
	s_mov_b64 s[16:17], 0
	v_add_f32_e32 v38, v37, v179
	v_fma_f32 v80, |v37|, v39, v184
	v_add_f32_e32 v37, v37, v185
	v_fma_f32 v65, |v40|, v39, v184
	v_fma_f32 v73, |v36|, v39, v184
	v_add_f32_e32 v40, v40, v185
	v_fma_f32 v88, |v38|, v39, v184
	v_add_f32_e32 v38, v38, v185
	v_fma_f32 v81, |v37|, v39, v184
	v_add_f32_e32 v36, v36, v185
	v_add_f32_e32 v37, v37, v185
	v_fma_f32 v66, |v40|, v39, v184
	v_add_f32_e32 v40, v40, v185
	v_fma_f32 v89, |v38|, v39, v184
	v_add_f32_e32 v38, v38, v185
	v_fma_f32 v74, |v36|, v39, v184
	v_fma_f32 v82, |v37|, v39, v184
	v_add_f32_e32 v36, v36, v185
	v_add_f32_e32 v37, v37, v185
	v_fma_f32 v67, |v40|, v39, v184
	v_fma_f32 v90, |v38|, v39, v184
	v_add_f32_e32 v38, v38, v185
	v_add_f32_e32 v40, v40, v185
	v_fma_f32 v75, |v36|, v39, v184
	v_fma_f32 v83, |v37|, v39, v184
	v_add_f32_e32 v36, v36, v185
	v_add_f32_e32 v37, v37, v185
	v_fma_f32 v91, |v38|, v39, v184
	v_add_f32_e32 v38, v38, v185
	v_fma_f32 v68, |v40|, v39, v184
	v_add_f32_e32 v40, v40, v185
	v_fma_f32 v76, |v36|, v39, v184
	v_fma_f32 v84, |v37|, v39, v184
	v_add_f32_e32 v36, v36, v185
	v_fma_f32 v92, |v38|, v39, v184
	v_add_f32_e32 v37, v37, v185
	v_add_f32_e32 v38, v38, v185
	v_fma_f32 v69, |v40|, v39, v184
	v_add_f32_e32 v40, v40, v185
	v_fma_f32 v77, |v36|, v39, v184
	v_add_f32_e32 v36, v36, v185
	v_fma_f32 v85, |v37|, v39, v184
	v_fma_f32 v93, |v38|, v39, v184
	v_add_f32_e32 v37, v37, v185
	v_add_f32_e32 v38, v38, v185
	v_fma_f32 v70, |v40|, v39, v184
	v_fma_f32 v78, |v36|, v39, v184
	v_add_f32_e32 v40, v40, v185
	v_add_f32_e32 v36, v36, v185
	v_fma_f32 v86, |v37|, v39, v184
	v_fma_f32 v94, |v38|, v39, v184
	v_add_f32_e32 v37, v37, v185
	v_add_f32_e32 v38, v38, v185
	v_fma_f32 v71, |v40|, v39, v184
	v_fma_f32 v79, |v36|, v39, v184
	v_fma_f32 v87, |v37|, v39, v184
	v_fma_f32 v95, |v38|, v39, v184
.LBB0_914:
	s_andn2_b64 vcc, exec, s[16:17]
	s_cbranch_vccnz .LBB0_916
	v_cndmask_b32_e64 v36, -v208, v208, s[10:11]
	v_mul_f32_e64 v64, v35, -v36
	v_mul_f32_e32 v35, 0x41800000, v36
	v_add_f32_e32 v72, v64, v35
	v_add_f32_e32 v65, v64, v36
	v_add_f32_e32 v80, v72, v35
	v_add_f32_e32 v73, v72, v36
	v_add_f32_e32 v66, v65, v36
	v_add_f32_e32 v88, v80, v35
	v_add_f32_e32 v81, v80, v36
	v_add_f32_e32 v74, v73, v36
	v_add_f32_e32 v67, v66, v36
	v_add_f32_e32 v89, v88, v36
	v_add_f32_e32 v82, v81, v36
	v_add_f32_e32 v75, v74, v36
	v_add_f32_e32 v68, v67, v36
	v_add_f32_e32 v90, v89, v36
	v_add_f32_e32 v83, v82, v36
	v_add_f32_e32 v76, v75, v36
	v_add_f32_e32 v69, v68, v36
	v_add_f32_e32 v91, v90, v36
	v_add_f32_e32 v84, v83, v36
	v_add_f32_e32 v77, v76, v36
	v_add_f32_e32 v70, v69, v36
	v_add_f32_e32 v92, v91, v36
	v_add_f32_e32 v85, v84, v36
	v_add_f32_e32 v78, v77, v36
	v_add_f32_e32 v71, v70, v36
	v_add_f32_e32 v93, v92, v36
	v_add_f32_e32 v86, v85, v36
	v_add_f32_e32 v79, v78, v36
	v_add_f32_e32 v94, v93, v36
	v_add_f32_e32 v87, v86, v36
	v_add_f32_e32 v95, v94, v36
.LBB0_916:
	s_and_b32 s3, s81, 0x3fffffc0
	s_lshl_b32 s3, s3, 2
	s_add_i32 s65, s3, 0
	s_add_i32 s65, s65, 0x1a400
	ds_read_b128 v[36:39], v217 offset:8736
	s_waitcnt lgkmcnt(2)
	v_mfma_f32_32x32x16_bf16 v[64:79], v[20:23], v[12:15], v[64:79]
	v_cmp_gt_u32_e64 s[10:11], 32, v203
	s_waitcnt lgkmcnt(1)
	v_mfma_f32_32x32x16_bf16 v[80:95], v[16:19], v[12:15], v[80:95]
	ds_read_b128 v[12:15], v217 offset:32
	ds_read_b128 v[16:19], v217 offset:64
	ds_read_b128 v[20:23], v217 offset:8768
	s_waitcnt lgkmcnt(2)
	v_mfma_f32_32x32x16_bf16 v[64:79], v[12:15], v[8:11], v[64:79]
	v_mfma_f32_32x32x16_bf16 v[80:95], v[36:39], v[8:11], v[80:95]
	ds_read_b128 v[8:11], v217 offset:96
	ds_read_b128 v[12:15], v217 offset:8800
	s_waitcnt lgkmcnt(3)
	v_mfma_f32_32x32x16_bf16 v[64:79], v[16:19], v[4:7], v[64:79]
	s_waitcnt lgkmcnt(2)
	v_mfma_f32_32x32x16_bf16 v[80:95], v[20:23], v[4:7], v[80:95]
	s_waitcnt lgkmcnt(1)
	v_mfma_f32_32x32x16_bf16 v[64:79], v[8:11], v[0:3], v[64:79]
	s_waitcnt lgkmcnt(0)
	v_mfma_f32_32x32x16_bf16 v[80:95], v[12:15], v[0:3], v[80:95]
	s_nop 15
	s_nop 7
	s_nop 0
	v_max3_f32 v0, v64, v80, v65
	v_max3_f32 v1, v81, v66, v82
	v_max3_f32 v0, v0, v67, v83
	v_max3_f32 v1, v1, v68, v84
	v_max3_f32 v0, v0, v69, v85
	v_max3_f32 v1, v1, v70, v86
	v_max3_f32 v0, v0, v71, v87
	v_max3_f32 v1, v1, v72, v88
	v_max3_f32 v0, v0, v73, v89
	v_max3_f32 v1, v1, v74, v90
	v_max3_f32 v0, v0, v75, v91
	v_max3_f32 v1, v1, v76, v92
	v_max3_f32 v0, v0, v77, v93
	v_max3_f32 v1, v1, v78, v94
	v_max3_f32 v0, v0, v79, v95
	v_max_f32_e32 v0, v0, v1
	v_mov_b32_e32 v1, v0
	s_nop 1
	v_permlane32_swap_b32_e32 v0, v1
	v_max_f32_e32 v16, v0, v1
	v_cmp_lt_f32_e32 vcc, s84, v16
	s_cmp_lg_u64 vcc, 0
	s_cselect_b64 s[16:17], -1, 0
	s_cbranch_vccz .LBB0_922
	v_max_f32_e32 v0, v16, v16
	v_max_f32_e32 v0, 0, v0
	v_exp_f32_e64 v1, -v0
	s_and_saveexec_b64 s[72:73], s[10:11]
	v_lshl_add_u32 v2, v202, 2, s65
	ds_write_b32 v2, v1
	s_or_b64 exec, exec, s[72:73]
	v_add_f32_e32 v218, 0, v0
	v_mul_f32_e32 v237, 0, v1
	v_sub_f32_e32 v79, v79, v0
	v_sub_f32_e32 v78, v78, v0
	v_sub_f32_e32 v77, v77, v0
	v_sub_f32_e32 v76, v76, v0
	v_sub_f32_e32 v75, v75, v0
	v_sub_f32_e32 v74, v74, v0
	v_sub_f32_e32 v73, v73, v0
	v_sub_f32_e32 v72, v72, v0
	v_sub_f32_e32 v71, v71, v0
	v_sub_f32_e32 v70, v70, v0
	v_sub_f32_e32 v69, v69, v0
	v_sub_f32_e32 v68, v68, v0
	v_sub_f32_e32 v67, v67, v0
	v_sub_f32_e32 v66, v66, v0
	v_sub_f32_e32 v65, v65, v0
	v_sub_f32_e32 v64, v64, v0
	v_sub_f32_e32 v95, v95, v0
	v_sub_f32_e32 v94, v94, v0
	v_sub_f32_e32 v93, v93, v0
	v_sub_f32_e32 v92, v92, v0
	v_sub_f32_e32 v91, v91, v0
	v_sub_f32_e32 v90, v90, v0
	v_sub_f32_e32 v89, v89, v0
	v_sub_f32_e32 v88, v88, v0
	v_sub_f32_e32 v87, v87, v0
	v_sub_f32_e32 v86, v86, v0
	v_sub_f32_e32 v85, v85, v0
	v_sub_f32_e32 v84, v84, v0
	v_sub_f32_e32 v83, v83, v0
	v_sub_f32_e32 v82, v82, v0
	v_sub_f32_e32 v81, v81, v0
	v_sub_f32_e32 v80, v80, v0
	s_andn2_b64 vcc, exec, s[16:17]
	v_add_u32_e32 v211, s65, v180
	s_cbranch_vccnz .LBB0_923

.LBB0_931:
	s_mul_hi_u32 s67, s96, 0xaaaaaaab
	s_lshr_b32 s67, s67, 1
	s_mul_i32 s76, s67, 0xcc00
	v_subrev_u32_e32 v96, s76, v223
	v_readlane_b32 s76, v213, s64
	s_lshl_b32 s78, s76, 6
	ds_read_b128 v[156:159], v210
	ds_read_b128 v[152:155], v210 offset:1024
	ds_read_b128 v[148:151], v210 offset:2048
	ds_read_b128 v[144:147], v210 offset:3072
	v_add_u32_e32 v176, s1, v222
	v_or_b32_e32 v97, s78, v209
	v_add_u32_e32 v239, v176, v96
	s_or_b32 s76, s78, 63
	v_sub_u32_e32 v97, v212, v97
	ds_read_b128 v[164:167], v239 offset:17408
	ds_read_b128 v[160:163], v239 offset:26112
	s_cmp_lt_i32 s76, s18
	v_cvt_f32_i32_e32 v168, v97
	s_cselect_b64 s[76:77], -1, 0
	s_cmp_gt_i32 s78, s7
	s_cselect_b64 s[78:79], -1, 0
	s_or_b64 s[78:79], s[76:77], s[78:79]
	s_andn2_b64 vcc, exec, s[78:79]
	s_mov_b64 s[78:79], -1
	s_cbranch_vccz .LBB0_933
	v_add_f32_e32 v97, v168, v179
	v_xor_b32_e32 v127, 0x80000000, v208
	v_add_f32_e32 v98, v97, v179
	v_add_f32_e32 v101, v97, v185
	v_xor_b32_e32 v169, 0x80000000, v218
	v_add_f32_e32 v99, v98, v179
	v_fma_f32 v112, |v98|, v127, v169
	v_add_f32_e32 v100, v168, v185
	v_add_f32_e32 v98, v98, v185
	v_fma_f32 v105, |v101|, v127, v169
	v_add_f32_e32 v101, v101, v185
	v_fma_f32 v120, |v99|, v127, v169
	v_add_f32_e32 v99, v99, v185
	v_fma_f32 v104, |v97|, v127, v169
	v_add_f32_e32 v102, v98, v185
	v_fma_f32 v97, |v100|, v127, v169
	v_add_f32_e32 v100, v100, v185
	v_fma_f32 v106, |v101|, v127, v169
	v_fma_f32 v121, |v99|, v127, v169
	v_add_f32_e32 v99, v99, v185
	v_fma_f32 v114, |v102|, v127, v169
	v_add_f32_e32 v101, v101, v185
	v_add_f32_e32 v102, v102, v185
	v_fma_f32 v113, |v98|, v127, v169
	v_fma_f32 v98, |v100|, v127, v169
	v_add_f32_e32 v103, v99, v185
	v_add_f32_e32 v100, v100, v185
	v_fma_f32 v107, |v101|, v127, v169
	v_fma_f32 v115, |v102|, v127, v169
	v_add_f32_e32 v101, v101, v185
	v_add_f32_e32 v102, v102, v185
	v_fma_f32 v123, |v103|, v127, v169
	v_add_f32_e32 v109, v100, v185
	v_add_f32_e32 v103, v103, v185
	v_fma_f32 v122, |v99|, v127, v169
	v_add_f32_e32 v111, v101, v185
	v_fma_f32 v99, |v100|, v127, v169
	v_fma_f32 v116, |v102|, v127, v169
	v_fma_f32 v100, |v109|, v127, v169
	v_fma_f32 v124, |v103|, v127, v169
	v_add_f32_e32 v110, v109, v185
	v_add_f32_e32 v102, v102, v185
	v_add_f32_e32 v103, v103, v185
	v_fma_f32 v109, |v111|, v127, v169
	v_add_f32_e32 v111, v111, v185
	v_fma_f32 v108, |v101|, v127, v169
	v_add_f32_e32 v119, v110, v185
	v_fma_f32 v101, |v110|, v127, v169
	v_fma_f32 v117, |v102|, v127, v169
	v_fma_f32 v125, |v103|, v127, v169
	v_add_f32_e32 v170, v102, v185
	v_add_f32_e32 v103, v103, v185
	v_fma_f32 v102, |v119|, v127, v169
	v_fma_f32 v110, |v111|, v127, v169
	v_add_f32_e32 v119, v119, v185
	v_add_f32_e32 v111, v111, v185
	v_fma_f32 v96, |v168|, v127, v169
	v_fma_f32 v118, |v170|, v127, v169
	v_fma_f32 v126, |v103|, v127, v169
	v_add_f32_e32 v170, v170, v185
	v_add_f32_e32 v171, v103, v185
	v_fma_f32 v103, |v119|, v127, v169
	v_fma_f32 v111, |v111|, v127, v169
	s_mov_b64 s[78:79], 0
	v_fma_f32 v119, |v170|, v127, v169
	v_fma_f32 v127, |v171|, v127, v169
.LBB0_933:
	s_andn2_b64 vcc, exec, s[78:79]
	s_cbranch_vccnz .LBB0_935
	v_cndmask_b32_e64 v127, -v208, v208, s[76:77]
	v_fma_f32 v96, v168, -v127, -v218
	v_mul_f32_e32 v97, 0x41800000, v127
	v_add_f32_e32 v104, v96, v97
	v_add_f32_e32 v112, v104, v97
	v_add_f32_e32 v105, v104, v127
	v_add_f32_e32 v120, v112, v97
	v_add_f32_e32 v97, v96, v127
	v_add_f32_e32 v113, v112, v127
	v_add_f32_e32 v106, v105, v127
	v_add_f32_e32 v121, v120, v127
	v_add_f32_e32 v98, v97, v127
	v_add_f32_e32 v114, v113, v127
	v_add_f32_e32 v107, v106, v127
	v_add_f32_e32 v122, v121, v127
	v_add_f32_e32 v99, v98, v127
	v_add_f32_e32 v115, v114, v127
	v_add_f32_e32 v108, v107, v127
	v_add_f32_e32 v123, v122, v127
	v_add_f32_e32 v100, v99, v127
	v_add_f32_e32 v116, v115, v127
	v_add_f32_e32 v109, v108, v127
	v_add_f32_e32 v124, v123, v127
	v_add_f32_e32 v101, v100, v127
	v_add_f32_e32 v117, v116, v127
	v_add_f32_e32 v110, v109, v127
	v_add_f32_e32 v125, v124, v127
	v_add_f32_e32 v102, v101, v127
	v_add_f32_e32 v118, v117, v127
	v_add_f32_e32 v111, v110, v127
	v_add_f32_e32 v126, v125, v127
	v_add_f32_e32 v103, v102, v127
	v_add_f32_e32 v119, v118, v127
	v_add_f32_e32 v127, v126, v127
.LBB0_935:
	s_mul_hi_u32 s76, s93, 0xaaaaaaab
	s_lshr_b32 s76, s76, 1
	s_mul_i32 s76, s76, 0xd800
	v_subrev_u32_e32 v190, s76, v219
	v_subrev_u32_e32 v191, s76, v227
	s_waitcnt lgkmcnt(1)
	v_mfma_f32_32x32x16_bf16 v[96:111], v[164:167], v[156:159], v[96:111]
	ds_read_b128 v[172:175], v239 offset:26144
	ds_read_b128 v[164:167], v239 offset:17440
	ds_read_b128 v[240:243], v239 offset:17472
	ds_read_b128 v[168:171], v239 offset:26176
	v_exp_f32_e32 v64, v64
	v_exp_f32_e32 v80, v80
	v_exp_f32_e32 v65, v65
	v_exp_f32_e32 v81, v81
	v_exp_f32_e32 v66, v66
	s_waitcnt lgkmcnt(2)
	v_mfma_f32_32x32x16_bf16 v[96:111], v[164:167], v[152:155], v[96:111]
	v_exp_f32_e32 v82, v82
	v_exp_f32_e32 v67, v67
	v_exp_f32_e32 v83, v83
	v_add_f32_e32 v192, v64, v80
	v_exp_f32_e32 v68, v68
	v_exp_f32_e32 v84, v84
	v_add_f32_e32 v192, 0, v192
	v_mfma_f32_32x32x16_bf16 v[112:127], v[160:163], v[156:159], v[112:127]
	v_add_f32_e32 v193, v65, v81
	v_exp_f32_e32 v69, v69
	v_exp_f32_e32 v85, v85
	v_add_f32_e32 v192, v193, v192
	v_add_f32_e32 v193, v66, v82
	v_exp_f32_e32 v70, v70
	v_exp_f32_e32 v86, v86
	s_waitcnt lgkmcnt(1)
	v_mfma_f32_32x32x16_bf16 v[96:111], v[240:243], v[148:151], v[96:111]
	v_add_f32_e32 v192, v193, v192
	v_add_f32_e32 v193, v67, v83
	v_exp_f32_e32 v71, v71
	v_exp_f32_e32 v87, v87
	v_add_f32_e32 v192, v193, v192
	v_add_f32_e32 v193, v68, v84
	v_exp_f32_e32 v72, v72
	v_mfma_f32_32x32x16_bf16 v[112:127], v[172:175], v[152:155], v[112:127]
	v_exp_f32_e32 v88, v88
	v_add_f32_e32 v192, v193, v192
	v_add_f32_e32 v193, v69, v85
	v_exp_f32_e32 v73, v73
	v_exp_f32_e32 v89, v89
	ds_read_b128 v[244:247], v239 offset:17504
	ds_read_b128 v[164:167], v239 offset:26208
	v_add_f32_e32 v192, v193, v192
	v_add_f32_e32 v193, v70, v86
	v_exp_f32_e32 v74, v74
	v_exp_f32_e32 v90, v90
	v_add_f32_e32 v192, v193, v192
	v_add_f32_e32 v193, v71, v87
	v_exp_f32_e32 v75, v75
	v_exp_f32_e32 v91, v91
	v_add_f32_e32 v192, v193, v192
	v_add_f32_e32 v193, v72, v88
	v_exp_f32_e32 v76, v76
	v_exp_f32_e32 v92, v92
	v_add_f32_e32 v192, v193, v192
	v_add_f32_e32 v193, v73, v89
	v_exp_f32_e32 v77, v77
	v_exp_f32_e32 v93, v93
	s_waitcnt lgkmcnt(1)
	v_mfma_f32_32x32x16_bf16 v[96:111], v[244:247], v[144:147], v[96:111]
	v_add_f32_e32 v192, v193, v192
	v_add_f32_e32 v193, v74, v90
	v_exp_f32_e32 v78, v78
	v_exp_f32_e32 v94, v94
	v_add_f32_e32 v192, v193, v192
	v_add_f32_e32 v193, v75, v91
	v_exp_f32_e32 v79, v79
	v_mfma_f32_32x32x16_bf16 v[112:127], v[168:171], v[148:151], v[112:127]
	v_exp_f32_e32 v95, v95
	v_add_f32_e32 v192, v193, v192
	v_add_f32_e32 v193, v76, v92
	v_add_f32_e32 v192, v193, v192
	v_add_f32_e32 v193, v77, v93
	v_add_f32_e32 v192, v193, v192
	v_add_f32_e32 v193, v78, v94
	v_add_f32_e32 v192, v193, v192
	v_add_f32_e32 v193, v79, v95
	v_add_f32_e32 v192, v193, v192
	v_add_f32_e32 v169, v237, v192
	v_cvt_pk_bf16_f32 v64, v64, v65
	v_cvt_pk_bf16_f32 v65, v66, v67
	v_cvt_pk_bf16_f32 v66, v68, v69
	v_cvt_pk_bf16_f32 v67, v70, v71
	v_cvt_pk_bf16_f32 v68, v72, v73
	v_cvt_pk_bf16_f32 v69, v74, v75
	v_cvt_pk_bf16_f32 v70, v76, v77
	v_cvt_pk_bf16_f32 v71, v78, v79
	v_cvt_pk_bf16_f32 v72, v80, v81
	v_cvt_pk_bf16_f32 v73, v82, v83
	v_cvt_pk_bf16_f32 v74, v84, v85
	v_cvt_pk_bf16_f32 v75, v86, v87
	v_cvt_pk_bf16_f32 v76, v88, v89
	v_cvt_pk_bf16_f32 v77, v90, v91
	v_cvt_pk_bf16_f32 v78, v92, v93
	v_cvt_pk_bf16_f32 v79, v94, v95
	v_add_u32_e32 v168, s66, v222
	v_add_u32_e32 v84, v168, v190
	ds_read_b128 v[80:83], v84 offset:52224
	v_add_u32_e32 v85, v168, v191
	s_waitcnt lgkmcnt(1)
	v_mfma_f32_32x32x16_bf16 v[112:127], v[164:167], v[144:147], v[112:127]
	s_cmp_gt_u32 s64, 1
	s_waitcnt lgkmcnt(0)
	v_mfma_f32_32x32x16_bf16 v[0:15], v[64:67], v[80:83], v[0:15]
	ds_read_b128 v[80:83], v84 offset:56832
	s_waitcnt lgkmcnt(0)
	v_mfma_f32_32x32x16_bf16 v[16:31], v[64:67], v[80:83], v[16:31]
	ds_read_b128 v[80:83], v85
	s_waitcnt lgkmcnt(0)
	v_mfma_f32_32x32x16_bf16 v[32:47], v[64:67], v[80:83], v[32:47]
	ds_read_b128 v[80:83], v85 offset:4608
	s_waitcnt lgkmcnt(0)
	v_mfma_f32_32x32x16_bf16 v[48:63], v[64:67], v[80:83], v[48:63]
	ds_read_b128 v[64:67], v84 offset:52256
	s_waitcnt lgkmcnt(0)
	v_mfma_f32_32x32x16_bf16 v[0:15], v[68:71], v[64:67], v[0:15]
	ds_read_b128 v[64:67], v84 offset:56864
	s_waitcnt lgkmcnt(0)
	v_mfma_f32_32x32x16_bf16 v[16:31], v[68:71], v[64:67], v[16:31]
	ds_read_b128 v[64:67], v85 offset:32
	s_waitcnt lgkmcnt(0)
	v_mfma_f32_32x32x16_bf16 v[32:47], v[68:71], v[64:67], v[32:47]
	ds_read_b128 v[64:67], v85 offset:4640
	s_waitcnt lgkmcnt(0)
	v_mfma_f32_32x32x16_bf16 v[48:63], v[68:71], v[64:67], v[48:63]
	ds_read_b128 v[64:67], v84 offset:52288
	s_waitcnt lgkmcnt(0)
	v_mfma_f32_32x32x16_bf16 v[0:15], v[72:75], v[64:67], v[0:15]
	ds_read_b128 v[64:67], v84 offset:56896
	s_waitcnt lgkmcnt(0)
	v_mfma_f32_32x32x16_bf16 v[16:31], v[72:75], v[64:67], v[16:31]
	ds_read_b128 v[64:67], v85 offset:64
	s_waitcnt lgkmcnt(0)
	v_mfma_f32_32x32x16_bf16 v[32:47], v[72:75], v[64:67], v[32:47]
	ds_read_b128 v[64:67], v85 offset:4672
	s_waitcnt lgkmcnt(0)
	v_mfma_f32_32x32x16_bf16 v[48:63], v[72:75], v[64:67], v[48:63]
	ds_read_b128 v[64:67], v84 offset:52320
	ds_read_b128 v[68:71], v84 offset:56928
	ds_read_b128 v[72:75], v85 offset:96
	ds_read_b128 v[80:83], v85 offset:4704
	s_nop 0
	s_waitcnt lgkmcnt(3)
	v_mfma_f32_32x32x16_bf16 v[0:15], v[76:79], v[64:67], v[0:15]
	v_max3_f32 v64, v96, v112, v97
	v_max3_f32 v65, v113, v98, v114
	v_max3_f32 v64, v64, v99, v115
	v_max3_f32 v65, v65, v100, v116
	v_max3_f32 v64, v64, v101, v117
	s_waitcnt lgkmcnt(2)
	v_mfma_f32_32x32x16_bf16 v[16:31], v[76:79], v[68:71], v[16:31]
	v_max3_f32 v65, v65, v102, v118
	v_max3_f32 v64, v64, v103, v119
	v_max3_f32 v65, v65, v104, v120
	v_max3_f32 v64, v64, v105, v121
	v_max3_f32 v65, v65, v106, v122
	s_waitcnt lgkmcnt(1)
	v_mfma_f32_32x32x16_bf16 v[32:47], v[76:79], v[72:75], v[32:47]
	v_max3_f32 v64, v64, v107, v123
	v_max3_f32 v65, v65, v108, v124
	v_max3_f32 v64, v64, v109, v125
	v_max3_f32 v65, v65, v110, v126
	v_max3_f32 v64, v64, v111, v127
	s_waitcnt lgkmcnt(0)
	v_mfma_f32_32x32x16_bf16 v[48:63], v[76:79], v[80:83], v[48:63]
	v_max_f32_e32 v64, v64, v65
	v_mov_b32_e32 v65, v64
	s_nop 1
	v_permlane32_swap_b32_e32 v64, v65
	v_max_f32_e32 v64, v64, v65
	s_cbranch_scc1 .LBB0_937
	v_add_f32_e32 v65, v218, v64
	v_max_f32_e32 v66, v220, v220
	s_cmp_lg_u32 s33, -1
	v_max_f32_e32 v220, v66, v65
	s_cbranch_scc0 .LBB0_961

.LBB0_947:
	s_add_i32 s24, s33, 3
	v_readlane_b32 s24, v213, s24
	v_subrev_u32_e32 v64, s65, v223
	s_lshl_b32 s24, s24, 6
	ds_read_b128 v[156:159], v210
	ds_read_b128 v[152:155], v210 offset:1024
	ds_read_b128 v[148:151], v210 offset:2048
	ds_read_b128 v[144:147], v210 offset:3072
	v_or_b32_e32 v65, s24, v209
	v_add_u32_e32 v170, v176, v64
	s_or_b32 s25, s24, 63
	v_sub_u32_e32 v65, v212, v65
	ds_read_b128 v[164:167], v170 offset:34816
	ds_read_b128 v[160:163], v170 offset:43520
	s_cmp_lt_i32 s25, s18
	v_cvt_f32_i32_e32 v171, v65
	s_cselect_b64 s[74:75], -1, 0
	s_cmp_gt_i32 s24, s7
	s_cselect_b64 s[24:25], -1, 0
	s_or_b64 s[24:25], s[74:75], s[24:25]
	s_andn2_b64 vcc, exec, s[24:25]
	s_mov_b64 s[76:77], -1
	s_cbranch_vccz .LBB0_949
	v_add_f32_e32 v65, v171, v179
	v_xor_b32_e32 v95, 0x80000000, v208
	s_waitcnt lgkmcnt(6)
	v_add_f32_e32 v66, v65, v179
	v_add_f32_e32 v69, v65, v185
	v_xor_b32_e32 v172, 0x80000000, v218
	v_add_f32_e32 v67, v66, v179
	v_fma_f32 v80, |v66|, v95, v172
	v_add_f32_e32 v68, v171, v185
	v_add_f32_e32 v66, v66, v185
	v_fma_f32 v73, |v69|, v95, v172
	v_add_f32_e32 v69, v69, v185
	v_fma_f32 v88, |v67|, v95, v172
	v_add_f32_e32 v67, v67, v185
	v_fma_f32 v72, |v65|, v95, v172
	v_add_f32_e32 v70, v66, v185
	v_fma_f32 v65, |v68|, v95, v172
	v_add_f32_e32 v68, v68, v185
	v_fma_f32 v74, |v69|, v95, v172
	v_fma_f32 v89, |v67|, v95, v172
	v_add_f32_e32 v67, v67, v185
	v_fma_f32 v82, |v70|, v95, v172
	v_add_f32_e32 v69, v69, v185
	v_add_f32_e32 v70, v70, v185
	v_fma_f32 v81, |v66|, v95, v172
	v_fma_f32 v66, |v68|, v95, v172
	v_add_f32_e32 v71, v67, v185
	v_add_f32_e32 v68, v68, v185
	v_fma_f32 v75, |v69|, v95, v172
	v_fma_f32 v83, |v70|, v95, v172
	v_add_f32_e32 v69, v69, v185
	v_add_f32_e32 v70, v70, v185
	v_fma_f32 v91, |v71|, v95, v172
	v_add_f32_e32 v77, v68, v185
	v_add_f32_e32 v71, v71, v185
	v_fma_f32 v90, |v67|, v95, v172
	v_add_f32_e32 v79, v69, v185
	v_fma_f32 v67, |v68|, v95, v172
	v_fma_f32 v84, |v70|, v95, v172
	v_fma_f32 v68, |v77|, v95, v172
	v_fma_f32 v92, |v71|, v95, v172
	v_add_f32_e32 v78, v77, v185
	v_add_f32_e32 v70, v70, v185
	v_add_f32_e32 v71, v71, v185
	v_fma_f32 v77, |v79|, v95, v172
	v_add_f32_e32 v79, v79, v185
	v_fma_f32 v76, |v69|, v95, v172
	v_add_f32_e32 v87, v78, v185
	v_fma_f32 v69, |v78|, v95, v172
	v_fma_f32 v85, |v70|, v95, v172
	v_fma_f32 v93, |v71|, v95, v172
	v_add_f32_e32 v173, v70, v185
	v_add_f32_e32 v71, v71, v185
	v_fma_f32 v70, |v87|, v95, v172
	v_fma_f32 v78, |v79|, v95, v172
	v_add_f32_e32 v87, v87, v185
	v_add_f32_e32 v79, v79, v185
	v_fma_f32 v64, |v171|, v95, v172
	v_fma_f32 v86, |v173|, v95, v172
	v_fma_f32 v94, |v71|, v95, v172
	v_add_f32_e32 v173, v173, v185
	v_add_f32_e32 v174, v71, v185
	v_fma_f32 v71, |v87|, v95, v172
	v_fma_f32 v79, |v79|, v95, v172
	s_mov_b64 s[76:77], 0
	v_fma_f32 v87, |v173|, v95, v172
	v_fma_f32 v95, |v174|, v95, v172
.LBB0_949:
	s_andn2_b64 vcc, exec, s[76:77]
	s_cbranch_vccnz .LBB0_951
	v_cndmask_b32_e64 v95, -v208, v208, s[74:75]
	v_fma_f32 v64, v171, -v95, -v218
	v_mul_f32_e32 v65, 0x41800000, v95
	v_add_f32_e32 v72, v64, v65
	v_add_f32_e32 v80, v72, v65
	v_add_f32_e32 v73, v72, v95
	v_add_f32_e32 v88, v80, v65
	v_add_f32_e32 v65, v64, v95
	v_add_f32_e32 v81, v80, v95
	v_add_f32_e32 v74, v73, v95
	v_add_f32_e32 v89, v88, v95
	s_waitcnt lgkmcnt(6)
	v_add_f32_e32 v66, v65, v95
	v_add_f32_e32 v82, v81, v95
	v_add_f32_e32 v75, v74, v95
	v_add_f32_e32 v90, v89, v95
	v_add_f32_e32 v67, v66, v95
	v_add_f32_e32 v83, v82, v95
	v_add_f32_e32 v76, v75, v95
	v_add_f32_e32 v91, v90, v95
	v_add_f32_e32 v68, v67, v95
	v_add_f32_e32 v84, v83, v95
	v_add_f32_e32 v77, v76, v95
	v_add_f32_e32 v92, v91, v95
	v_add_f32_e32 v69, v68, v95
	v_add_f32_e32 v85, v84, v95
	v_add_f32_e32 v78, v77, v95
	v_add_f32_e32 v93, v92, v95
	v_add_f32_e32 v70, v69, v95
	v_add_f32_e32 v86, v85, v95
	v_add_f32_e32 v79, v78, v95
	v_add_f32_e32 v94, v93, v95
	v_add_f32_e32 v71, v70, v95
	v_add_f32_e32 v87, v86, v95
	v_add_f32_e32 v95, v94, v95
.LBB0_951:
	s_mul_i32 s67, s67, 0xd800
	v_subrev_u32_e32 v171, s67, v228
	v_subrev_u32_e32 v192, s67, v229
	v_subrev_u32_e32 v193, s67, v230
	v_subrev_u32_e32 v238, s67, v231
	v_subrev_u32_e32 v239, s67, v232
	v_subrev_u32_e32 v240, s67, v233
	v_subrev_u32_e32 v241, s67, v234
	v_subrev_u32_e32 v242, s67, v235
	v_subrev_u32_e32 v243, s67, v236
	v_exp_f32_e32 v244, v96
	v_exp_f32_e32 v245, v112
	v_exp_f32_e32 v176, v97
	v_exp_f32_e32 v112, v113
	v_exp_f32_e32 v246, v114
	v_add_f32_e32 v113, v245, v244
	v_exp_f32_e32 v114, v115
	v_pk_add_f32 v[96:97], v[112:113], v[176:177]
	v_exp_f32_e32 v113, v98
	v_pk_add_f32 v[172:173], v[96:97], v[96:97] op_sel_hi:[0,1]
	v_exp_f32_e32 v172, v99
	s_waitcnt lgkmcnt(1)
	v_mfma_f32_32x32x16_bf16 v[64:79], v[164:167], v[156:159], v[64:79]
	v_add_f32_e32 v115, v246, v113
	v_add_f32_e64 v96, v114, v172
	v_add_f32_e64 v97, v115, v173
	v_add_f32_e64 v174, v96, v96
	v_add_f32_e64 v175, v96, v97
	v_exp_f32_e32 v115, v100
	v_exp_f32_e32 v173, v116
	ds_read_b128 v[96:99], v170 offset:34848
	v_exp_f32_e32 v174, v101
	v_exp_f32_e32 v116, v117
	v_add_f32_e32 v117, v173, v115
	s_waitcnt lgkmcnt(1)
	v_mfma_f32_32x32x16_bf16 v[80:95], v[160:163], v[156:159], v[80:95]
	v_add_f32_e64 v100, v116, v174
	v_add_f32_e64 v101, v117, v175
	v_add_f32_e64 v164, v100, v100
	v_add_f32_e64 v165, v100, v101
	v_exp_f32_e32 v117, v102
	v_exp_f32_e32 v175, v118
	v_exp_f32_e32 v164, v103
	v_exp_f32_e32 v118, v119
	ds_read_b128 v[100:103], v170 offset:34880
	s_waitcnt lgkmcnt(1)
	v_mfma_f32_32x32x16_bf16 v[64:79], v[96:99], v[152:155], v[64:79]
	v_add_f32_e32 v119, v175, v117
	v_add_f32_e64 v96, v118, v164
	v_add_f32_e64 v97, v119, v165
	v_exp_f32_e32 v119, v104
	v_pk_add_f32 v[166:167], v[96:97], v[96:97] op_sel_hi:[0,1]
	v_exp_f32_e32 v165, v120
	v_exp_f32_e32 v166, v105
	v_exp_f32_e32 v120, v121
	ds_read_b128 v[96:99], v170 offset:34912
	v_add_f32_e32 v121, v165, v119
	s_waitcnt lgkmcnt(1)
	v_mfma_f32_32x32x16_bf16 v[64:79], v[100:103], v[148:151], v[64:79]
	v_add_f32_e64 v100, v120, v166
	v_add_f32_e64 v101, v121, v167
	v_exp_f32_e32 v121, v106
	v_pk_add_f32 v[190:191], v[100:101], v[100:101] op_sel_hi:[0,1]
	ds_read_b128 v[100:103], v170 offset:43552
	v_exp_f32_e32 v167, v122
	v_exp_f32_e32 v190, v107
	v_exp_f32_e32 v122, v123
	s_waitcnt lgkmcnt(1)
	v_mfma_f32_32x32x16_bf16 v[64:79], v[96:99], v[144:147], v[64:79]
	v_add_f32_e32 v123, v167, v121
	v_add_f32_e64 v96, v122, v190
	v_add_f32_e64 v97, v123, v191
	v_add_f32_e64 v106, v96, v96
	v_add_f32_e64 v107, v96, v97
	ds_read_b128 v[96:99], v170 offset:43584
	v_exp_f32_e32 v123, v108
	v_exp_f32_e32 v191, v124
	s_waitcnt lgkmcnt(1)
	v_mfma_f32_32x32x16_bf16 v[80:95], v[100:103], v[152:155], v[80:95]
	v_exp_f32_e32 v106, v109
	v_exp_f32_e32 v124, v125
	v_add_f32_e32 v125, v191, v123
	ds_read_b128 v[100:103], v170 offset:43616
	v_pk_add_f32 v[104:105], v[124:125], v[106:107]
	s_nop 0
	v_pk_add_f32 v[108:109], v[104:105], v[104:105] op_sel_hi:[0,1]
	v_exp_f32_e32 v107, v110
	v_exp_f32_e32 v125, v126
	s_waitcnt lgkmcnt(1)
	v_mfma_f32_32x32x16_bf16 v[80:95], v[96:99], v[148:151], v[80:95]
	v_exp_f32_e32 v108, v111
	v_exp_f32_e32 v126, v127
	v_add_f32_e32 v127, v125, v107
	v_pk_add_f32 v[104:105], v[126:127], v[108:109]
	s_nop 0
	v_add_f32_e32 v104, v104, v105
	v_add_f32_e32 v237, v169, v104
	v_cvt_pk_bf16_f32 v96, v244, v176
	v_cvt_pk_bf16_f32 v97, v113, v172
	v_cvt_pk_bf16_f32 v98, v115, v174
	v_cvt_pk_bf16_f32 v99, v117, v164
	v_cvt_pk_bf16_f32 v104, v119, v166
	v_cvt_pk_bf16_f32 v105, v121, v190
	v_cvt_pk_bf16_f32 v106, v123, v106
	v_cvt_pk_bf16_f32 v107, v107, v108
	v_cvt_pk_bf16_f32 v108, v245, v112
	v_cvt_pk_bf16_f32 v109, v246, v114
	v_cvt_pk_bf16_f32 v110, v173, v116
	v_cvt_pk_bf16_f32 v111, v175, v118
	v_cvt_pk_bf16_f32 v112, v165, v120
	v_cvt_pk_bf16_f32 v113, v167, v122
	v_cvt_pk_bf16_f32 v114, v191, v124
	v_cvt_pk_bf16_f32 v115, v125, v126
	v_add_u32_e32 v116, v168, v239
	ds_read_b128 v[116:119], v116
	s_waitcnt lgkmcnt(1)
	v_mfma_f32_32x32x16_bf16 v[80:95], v[100:103], v[144:147], v[80:95]
	s_waitcnt lgkmcnt(0)
	v_mfma_f32_32x32x16_bf16 v[0:15], v[96:99], v[116:119], v[0:15]
	v_add_u32_e32 v116, v168, v243
	ds_read_b128 v[116:119], v116
	s_waitcnt lgkmcnt(0)
	v_mfma_f32_32x32x16_bf16 v[16:31], v[96:99], v[116:119], v[16:31]
	v_add_u32_e32 v116, v168, v242
	ds_read_b128 v[100:103], v116
	s_waitcnt lgkmcnt(0)
	v_mfma_f32_32x32x16_bf16 v[32:47], v[96:99], v[100:103], v[32:47]
	ds_read_b128 v[100:103], v116 offset:4608
	s_waitcnt lgkmcnt(0)
	v_mfma_f32_32x32x16_bf16 v[48:63], v[96:99], v[100:103], v[48:63]
	v_add_u32_e32 v96, v168, v241
	ds_read_b128 v[96:99], v96
	s_waitcnt lgkmcnt(0)
	v_mfma_f32_32x32x16_bf16 v[0:15], v[104:107], v[96:99], v[0:15]
	v_add_u32_e32 v96, v168, v240
	ds_read_b128 v[96:99], v96
	s_waitcnt lgkmcnt(0)
	v_mfma_f32_32x32x16_bf16 v[16:31], v[104:107], v[96:99], v[16:31]
	ds_read_b128 v[96:99], v116 offset:32
	s_waitcnt lgkmcnt(0)
	v_mfma_f32_32x32x16_bf16 v[32:47], v[104:107], v[96:99], v[32:47]
	ds_read_b128 v[96:99], v116 offset:4640
	s_waitcnt lgkmcnt(0)
	v_mfma_f32_32x32x16_bf16 v[48:63], v[104:107], v[96:99], v[48:63]
	v_add_u32_e32 v96, v168, v238
	ds_read_b128 v[96:99], v96
	s_waitcnt lgkmcnt(0)
	v_mfma_f32_32x32x16_bf16 v[0:15], v[108:111], v[96:99], v[0:15]
	v_add_u32_e32 v96, v168, v193
	ds_read_b128 v[96:99], v96
	s_waitcnt lgkmcnt(0)
	v_mfma_f32_32x32x16_bf16 v[16:31], v[108:111], v[96:99], v[16:31]
	ds_read_b128 v[96:99], v116 offset:64
	s_waitcnt lgkmcnt(0)
	v_mfma_f32_32x32x16_bf16 v[32:47], v[108:111], v[96:99], v[32:47]
	ds_read_b128 v[96:99], v116 offset:4672
	ds_read_b128 v[100:103], v116 offset:96
	ds_read_b128 v[104:107], v116 offset:4704
	s_waitcnt lgkmcnt(2)
	v_mfma_f32_32x32x16_bf16 v[48:63], v[108:111], v[96:99], v[48:63]
	v_add_u32_e32 v96, v168, v192
	v_add_u32_e32 v108, v168, v171
	ds_read_b128 v[96:99], v96
	ds_read_b128 v[108:111], v108
	s_nop 0
	s_nop 0
	v_max3_f32 v116, v64, v80, v65
	v_max3_f32 v117, v81, v66, v82
	s_waitcnt lgkmcnt(1)
	v_mfma_f32_32x32x16_bf16 v[0:15], v[112:115], v[96:99], v[0:15]
	v_max3_f32 v96, v116, v67, v83
	v_max3_f32 v97, v117, v68, v84
	v_max3_f32 v96, v96, v69, v85
	v_max3_f32 v97, v97, v70, v86
	v_max3_f32 v96, v96, v71, v87
	v_max3_f32 v97, v97, v72, v88
	s_waitcnt lgkmcnt(0)
	v_mfma_f32_32x32x16_bf16 v[16:31], v[112:115], v[108:111], v[16:31]
	v_max3_f32 v96, v96, v73, v89
	v_max3_f32 v97, v97, v74, v90
	v_max3_f32 v96, v96, v75, v91
	v_max3_f32 v97, v97, v76, v92
	v_max3_f32 v96, v96, v77, v93
	v_mfma_f32_32x32x16_bf16 v[32:47], v[112:115], v[100:103], v[32:47]
	v_max3_f32 v97, v97, v78, v94
	v_max3_f32 v96, v96, v79, v95
	v_max_f32_e32 v96, v96, v97
	v_mov_b32_e32 v97, v96
	s_nop 1
	v_permlane32_swap_b32_e32 v96, v97
	v_mfma_f32_32x32x16_bf16 v[48:63], v[112:115], v[104:107], v[48:63]
	v_max_f32_e32 v96, v96, v97
	v_cmp_lt_f32_e32 vcc, s84, v96
	s_cmp_lg_u64 vcc, 0
	s_cselect_b64 s[74:75], -1, 0
	s_cbranch_vccz .LBB0_955
	v_max_f32_e32 v96, v96, v96
	v_max_f32_e32 v96, 0, v96
	v_exp_f32_e64 v97, -v96
	s_and_saveexec_b64 s[76:77], s[10:11]
	ds_write_b32 v214, v97
	s_or_b64 exec, exec, s[76:77]
	v_add_f32_e32 v218, v218, v96
	v_mul_f32_e32 v237, v237, v97
	v_sub_f32_e32 v79, v79, v96
	v_sub_f32_e32 v78, v78, v96
	v_sub_f32_e32 v77, v77, v96
	v_sub_f32_e32 v76, v76, v96
	v_sub_f32_e32 v75, v75, v96
	v_sub_f32_e32 v74, v74, v96
	v_sub_f32_e32 v73, v73, v96
	v_sub_f32_e32 v72, v72, v96
	v_sub_f32_e32 v71, v71, v96
	v_sub_f32_e32 v70, v70, v96
	v_sub_f32_e32 v69, v69, v96
	v_sub_f32_e32 v68, v68, v96
	v_sub_f32_e32 v67, v67, v96
	v_sub_f32_e32 v66, v66, v96
	v_sub_f32_e32 v65, v65, v96
	v_sub_f32_e32 v64, v64, v96
	v_sub_f32_e32 v95, v95, v96
	v_sub_f32_e32 v94, v94, v96
	v_sub_f32_e32 v93, v93, v96
	v_sub_f32_e32 v92, v92, v96
	v_sub_f32_e32 v91, v91, v96
	v_sub_f32_e32 v90, v90, v96
	v_sub_f32_e32 v89, v89, v96
	v_sub_f32_e32 v88, v88, v96
	v_sub_f32_e32 v87, v87, v96
	v_sub_f32_e32 v86, v86, v96
	v_sub_f32_e32 v85, v85, v96
	v_sub_f32_e32 v84, v84, v96
	v_sub_f32_e32 v83, v83, v96
	v_sub_f32_e32 v82, v82, v96
	v_sub_f32_e32 v81, v81, v96
	v_sub_f32_e32 v80, v80, v96

; #define ATT_PERIOD(CUR0, CUR1, PRV0, PRV1, t_) do { ATT_STAGE(t_); ATT_QK(CUR0, CUR1, t_); ATT_FIN(PRV0, PRV1); __builtin_amdgcn_sched_barrier(0); \
;         ATT_PV((t_) - 1); ATT_PART(CUR0, CUR1, t_); __builtin_amdgcn_sched_barrier(0); ATT_RESC(); ATT_BAR(); } while (0)
; __device__ __forceinline__ void attn_unit(LAS unsigned char* lds, const bf16* Qh, const bf16* Kh, const bf16* VTh, const float* nrm, bf16* Y, const float* subln, float lam, int b, int h, int qb) {
;     ...
;       if (t < T) { ATT_PERIOD(sB0, sB1, sA0, sA1, t); ATT_FIN(sB0, sB1); ATT_PV(T - 1); }
.LBB0_966:
	s_andn2_b64 vcc, exec, s[12:13]
	s_cbranch_vccnz .LBB0_978
	s_mul_hi_u32 s1, s0, 0xaaaaaaab
	s_lshr_b32 s1, s1, 1
	s_mul_i32 s1, s1, 3
	s_sub_i32 s1, s0, s1
	v_readlane_b32 s0, v213, s0
	s_lshl_b32 s0, s0, 6
	s_mulk_i32 s1, 0x4400
	ds_read_b128 v[108:111], v210
	ds_read_b128 v[104:107], v210 offset:1024
	ds_read_b128 v[100:103], v210 offset:2048
	ds_read_b128 v[96:99], v210 offset:3072
	v_or_b32_e32 v64, s0, v209
	v_add_u32_e32 v120, s1, v217
	s_or_b32 s1, s0, 63
	v_sub_u32_e32 v64, v212, v64
	ds_read_b128 v[116:119], v120
	ds_read_b128 v[112:115], v120 offset:8704
	s_cmp_lt_i32 s1, s18
	v_cvt_f32_i32_e32 v121, v64
	s_cselect_b64 s[12:13], -1, 0
	s_cmp_gt_i32 s0, s7
	s_cselect_b64 s[0:1], -1, 0
	s_or_b64 s[0:1], s[12:13], s[0:1]
	s_andn2_b64 vcc, exec, s[0:1]
	s_mov_b64 s[16:17], -1
	s_cbranch_vccz .LBB0_969
	v_add_f32_e32 v65, v121, v179
	v_xor_b32_e32 v95, 0x80000000, v208
	v_add_f32_e32 v66, v65, v179
	v_add_f32_e32 v69, v65, v185
	v_xor_b32_e32 v122, 0x80000000, v218
	v_add_f32_e32 v67, v66, v179
	v_fma_f32 v80, |v66|, v95, v122
	v_add_f32_e32 v68, v121, v185
	v_add_f32_e32 v66, v66, v185
	v_fma_f32 v73, |v69|, v95, v122
	v_add_f32_e32 v69, v69, v185
	v_fma_f32 v88, |v67|, v95, v122
	v_add_f32_e32 v67, v67, v185
	v_fma_f32 v72, |v65|, v95, v122
	v_add_f32_e32 v70, v66, v185
	v_fma_f32 v65, |v68|, v95, v122
	v_add_f32_e32 v68, v68, v185
	v_fma_f32 v74, |v69|, v95, v122
	v_fma_f32 v89, |v67|, v95, v122
	v_add_f32_e32 v67, v67, v185
	v_fma_f32 v82, |v70|, v95, v122
	v_add_f32_e32 v69, v69, v185
	v_add_f32_e32 v70, v70, v185
	v_fma_f32 v81, |v66|, v95, v122
	v_fma_f32 v66, |v68|, v95, v122
	v_add_f32_e32 v71, v67, v185
	v_add_f32_e32 v68, v68, v185
	v_fma_f32 v75, |v69|, v95, v122
	v_fma_f32 v83, |v70|, v95, v122
	v_add_f32_e32 v69, v69, v185
	v_add_f32_e32 v70, v70, v185
	v_fma_f32 v91, |v71|, v95, v122
	v_add_f32_e32 v77, v68, v185
	v_add_f32_e32 v71, v71, v185
	v_fma_f32 v90, |v67|, v95, v122
	v_add_f32_e32 v79, v69, v185
	v_fma_f32 v67, |v68|, v95, v122
	v_fma_f32 v84, |v70|, v95, v122
	v_fma_f32 v68, |v77|, v95, v122
	v_fma_f32 v92, |v71|, v95, v122
	v_add_f32_e32 v78, v77, v185
	v_add_f32_e32 v70, v70, v185
	v_add_f32_e32 v71, v71, v185
	v_fma_f32 v77, |v79|, v95, v122
	v_add_f32_e32 v79, v79, v185
	v_fma_f32 v76, |v69|, v95, v122
	v_add_f32_e32 v87, v78, v185
	v_fma_f32 v69, |v78|, v95, v122
	v_fma_f32 v85, |v70|, v95, v122
	v_fma_f32 v93, |v71|, v95, v122
	v_add_f32_e32 v123, v70, v185
	v_add_f32_e32 v71, v71, v185
	v_fma_f32 v70, |v87|, v95, v122
	v_fma_f32 v78, |v79|, v95, v122
	v_add_f32_e32 v87, v87, v185
	v_add_f32_e32 v79, v79, v185
	v_fma_f32 v64, |v121|, v95, v122
	v_fma_f32 v86, |v123|, v95, v122
	v_fma_f32 v94, |v71|, v95, v122
	v_add_f32_e32 v123, v123, v185
	v_add_f32_e32 v124, v71, v185
	v_fma_f32 v71, |v87|, v95, v122
	v_fma_f32 v79, |v79|, v95, v122
	s_mov_b64 s[16:17], 0
	v_fma_f32 v87, |v123|, v95, v122
	v_fma_f32 v95, |v124|, v95, v122
.LBB0_969:
	s_andn2_b64 vcc, exec, s[16:17]
	s_cbranch_vccnz .LBB0_971
	v_cndmask_b32_e64 v95, -v208, v208, s[12:13]
	v_fma_f32 v64, v121, -v95, -v218
	v_mul_f32_e32 v65, 0x41800000, v95
	v_add_f32_e32 v72, v64, v65
	v_add_f32_e32 v80, v72, v65
	v_add_f32_e32 v73, v72, v95
	v_add_f32_e32 v88, v80, v65
	v_add_f32_e32 v65, v64, v95
	v_add_f32_e32 v81, v80, v95
	v_add_f32_e32 v74, v73, v95
	v_add_f32_e32 v89, v88, v95
	v_add_f32_e32 v66, v65, v95
	v_add_f32_e32 v82, v81, v95
	v_add_f32_e32 v75, v74, v95
	v_add_f32_e32 v90, v89, v95
	v_add_f32_e32 v67, v66, v95
	v_add_f32_e32 v83, v82, v95
	v_add_f32_e32 v76, v75, v95
	v_add_f32_e32 v91, v90, v95
	v_add_f32_e32 v68, v67, v95
	v_add_f32_e32 v84, v83, v95
	v_add_f32_e32 v77, v76, v95
	v_add_f32_e32 v92, v91, v95
	v_add_f32_e32 v69, v68, v95
	v_add_f32_e32 v85, v84, v95
	v_add_f32_e32 v78, v77, v95
	v_add_f32_e32 v93, v92, v95
	v_add_f32_e32 v70, v69, v95
	v_add_f32_e32 v86, v85, v95
	v_add_f32_e32 v79, v78, v95
	v_add_f32_e32 v94, v93, v95
	v_add_f32_e32 v71, v70, v95
	v_add_f32_e32 v87, v86, v95
	v_add_f32_e32 v95, v94, v95
.LBB0_971:
	s_waitcnt lgkmcnt(1)
	v_mfma_f32_32x32x16_bf16 v[64:79], v[116:119], v[108:111], v[64:79]
	v_add_f32_e32 v129, v159, v162
	ds_read_b128 v[122:125], v120 offset:32
	ds_read_b128 v[190:193], v120 offset:64
	ds_read_b128 v[216:219], v120 offset:8736
	ds_read_b128 v[220:223], v120 offset:96
	ds_read_b128 v[224:227], v120 offset:8768
	ds_read_b128 v[228:231], v120 offset:8800
	v_pk_add_f32 v[116:117], v[128:129], v[176:177]
	v_add_f32_e32 v131, v160, v164
	v_pk_add_f32 v[116:117], v[116:117], v[116:117] op_sel_hi:[0,1]
	v_mov_b32_e32 v139, v117
	v_pk_add_f32 v[116:117], v[130:131], v[138:139]
	s_waitcnt lgkmcnt(5)
	v_mfma_f32_32x32x16_bf16 v[64:79], v[122:125], v[104:107], v[64:79]
	v_pk_add_f32 v[116:117], v[116:117], v[116:117] op_sel_hi:[0,1]
	v_add_f32_e32 v133, v161, v166
	v_mov_b32_e32 v141, v117
	v_pk_add_f32 v[116:117], v[132:133], v[140:141]
	v_add_f32_e32 v135, v163, v168
	v_pk_add_f32 v[116:117], v[116:117], v[116:117] op_sel_hi:[0,1]
	v_mov_b32_e32 v145, v117
	v_mfma_f32_32x32x16_bf16 v[80:95], v[112:115], v[108:111], v[80:95]
	v_add_f32_e64 v116, v134, v144
	v_add_f32_e64 v117, v135, v145
	v_add_f32_e32 v137, v165, v170
	v_pk_add_f32 v[116:117], v[116:117], v[116:117] op_sel_hi:[0,1]
	v_mov_b32_e32 v149, v117
	v_pk_add_f32 v[116:117], v[136:137], v[148:149]
	v_add_f32_e32 v143, v167, v172
	v_pk_add_f32 v[116:117], v[116:117], v[116:117] op_sel_hi:[0,1]
	s_waitcnt lgkmcnt(4)
	v_mfma_f32_32x32x16_bf16 v[64:79], v[190:193], v[100:103], v[64:79]
	v_mov_b32_e32 v153, v117
	v_add_f32_e64 v116, v142, v152
	v_add_f32_e64 v117, v143, v153
	v_add_f32_e32 v147, v169, v173
	v_pk_add_f32 v[116:117], v[116:117], v[116:117] op_sel_hi:[0,1]
	v_mov_b32_e32 v155, v117
	v_pk_add_f32 v[116:117], v[146:147], v[154:155]
	v_add_f32_e32 v151, v171, v174
	s_waitcnt lgkmcnt(3)
	v_mfma_f32_32x32x16_bf16 v[80:95], v[216:219], v[104:107], v[80:95]
	v_pk_add_f32 v[116:117], v[116:117], v[116:117] op_sel_hi:[0,1]
	v_mov_b32_e32 v157, v117
	v_pk_add_f32 v[108:109], v[150:151], v[156:157]
	s_nop 0
	v_add_f32_e32 v108, v108, v109
	v_add_f32_e32 v108, v237, v108
	s_waitcnt lgkmcnt(2)
	v_mfma_f32_32x32x16_bf16 v[64:79], v[220:223], v[96:99], v[64:79]
	v_cvt_pk_bf16_f32 v110, v162, v176
	v_cvt_pk_bf16_f32 v111, v164, v138
	v_cvt_pk_bf16_f32 v112, v166, v140
	v_cvt_pk_bf16_f32 v113, v168, v144
	v_cvt_pk_bf16_f32 v104, v170, v148
	v_cvt_pk_bf16_f32 v105, v172, v152
	v_cvt_pk_bf16_f32 v106, v173, v154
	s_waitcnt lgkmcnt(1)
	v_mfma_f32_32x32x16_bf16 v[80:95], v[224:227], v[100:103], v[80:95]
	v_cvt_pk_bf16_f32 v107, v174, v156
	v_cvt_pk_bf16_f32 v114, v159, v128
	v_cvt_pk_bf16_f32 v115, v160, v130
	v_cvt_pk_bf16_f32 v116, v161, v132
	v_cvt_pk_bf16_f32 v117, v163, v134
	v_cvt_pk_bf16_f32 v100, v165, v136
	v_cvt_pk_bf16_f32 v101, v167, v142
	v_cvt_pk_bf16_f32 v102, v169, v146
	v_cvt_pk_bf16_f32 v103, v171, v150
	s_add_i32 s64, s64, 1
	s_mul_hi_u32 s0, s64, 0xaaaaaaab
	s_lshr_b32 s0, s0, 1
	s_mul_i32 s0, s0, 3
	s_sub_i32 s0, s64, s0
	s_mulk_i32 s0, 0x4800
	v_add_u32_e32 v109, s0, v158
	ds_read_b128 v[118:121], v109 offset:52224
	ds_read_b128 v[122:125], v109 offset:52256
	s_waitcnt lgkmcnt(2)
	v_mfma_f32_32x32x16_bf16 v[80:95], v[228:231], v[96:99], v[80:95]
	v_add_u32_e32 v134, 0xcc00, v109
	s_waitcnt lgkmcnt(1)
	v_mfma_f32_32x32x16_bf16 v[0:15], v[110:113], v[118:121], v[0:15]
	ds_read_b128 v[118:121], v109 offset:56832
	ds_read_b128 v[126:129], v109 offset:56864
	s_waitcnt lgkmcnt(1)
	v_mfma_f32_32x32x16_bf16 v[16:31], v[110:113], v[118:121], v[16:31]
	ds_read_b128 v[96:99], v109 offset:61440
	ds_read_b128 v[118:121], v109 offset:61472
	s_waitcnt lgkmcnt(1)
	v_mfma_f32_32x32x16_bf16 v[32:47], v[110:113], v[96:99], v[32:47]
	ds_read_b128 v[96:99], v134 offset:13824
	ds_read_b128 v[130:133], v134 offset:13856
	s_waitcnt lgkmcnt(1)
	v_mfma_f32_32x32x16_bf16 v[48:63], v[110:113], v[96:99], v[48:63]
	v_mfma_f32_32x32x16_bf16 v[0:15], v[104:107], v[122:125], v[0:15]
	v_mfma_f32_32x32x16_bf16 v[16:31], v[104:107], v[126:129], v[16:31]
	v_mfma_f32_32x32x16_bf16 v[32:47], v[104:107], v[118:121], v[32:47]
	s_waitcnt lgkmcnt(0)
	v_mfma_f32_32x32x16_bf16 v[48:63], v[104:107], v[130:133], v[48:63]
	ds_read_b128 v[96:99], v109 offset:52288
	ds_read_b128 v[104:107], v109 offset:52320
	s_waitcnt lgkmcnt(1)
	v_mfma_f32_32x32x16_bf16 v[0:15], v[114:117], v[96:99], v[0:15]
	ds_read_b128 v[96:99], v109 offset:56896
	ds_read_b128 v[110:113], v109 offset:56928
	s_waitcnt lgkmcnt(1)
	v_mfma_f32_32x32x16_bf16 v[16:31], v[114:117], v[96:99], v[16:31]
	ds_read_b128 v[96:99], v109 offset:61504
	ds_read_b128 v[118:121], v109 offset:61536
	s_waitcnt lgkmcnt(1)
	v_mfma_f32_32x32x16_bf16 v[32:47], v[114:117], v[96:99], v[32:47]
	ds_read_b128 v[96:99], v134 offset:13888
	ds_read_b128 v[122:125], v134 offset:13920
	s_nop 0
	s_waitcnt lgkmcnt(1)
	v_mfma_f32_32x32x16_bf16 v[48:63], v[114:117], v[96:99], v[48:63]
	v_max3_f32 v96, v64, v80, v65
	v_max3_f32 v97, v81, v66, v82
	v_max3_f32 v96, v96, v67, v83
	v_max3_f32 v97, v97, v68, v84
	v_max3_f32 v96, v96, v69, v85
	v_max3_f32 v97, v97, v70, v86
	v_mfma_f32_32x32x16_bf16 v[0:15], v[100:103], v[104:107], v[0:15]
	v_max3_f32 v96, v96, v71, v87
	v_max3_f32 v97, v97, v72, v88
	v_max3_f32 v96, v96, v73, v89
	v_max3_f32 v97, v97, v74, v90
	v_max3_f32 v96, v96, v75, v91
	v_mfma_f32_32x32x16_bf16 v[16:31], v[100:103], v[110:113], v[16:31]
	v_max3_f32 v97, v97, v76, v92
	v_max3_f32 v96, v96, v77, v93
	v_max3_f32 v97, v97, v78, v94
	v_max3_f32 v96, v96, v79, v95
	v_max_f32_e32 v96, v96, v97
	v_mfma_f32_32x32x16_bf16 v[32:47], v[100:103], v[118:121], v[32:47]
	v_mov_b32_e32 v97, v96
	s_nop 1
	v_permlane32_swap_b32_e32 v96, v97
	v_max_f32_e32 v96, v96, v97
	v_cmp_lt_f32_e32 vcc, s84, v96
	s_cmp_lg_u64 vcc, 0
	s_waitcnt lgkmcnt(0)
	v_mfma_f32_32x32x16_bf16 v[48:63], v[100:103], v[122:125], v[48:63]
	s_cselect_b64 s[12:13], -1, 0
	s_cbranch_vccz .LBB0_975
	v_max_f32_e32 v96, v96, v96
	v_max_f32_e32 v96, 0, v96
	v_exp_f32_e64 v97, -v96
	s_and_saveexec_b64 s[16:17], s[10:11]
	ds_write_b32 v214, v97
	s_or_b64 exec, exec, s[16:17]
	v_mul_f32_e32 v108, v108, v97
	v_sub_f32_e32 v79, v79, v96
	v_sub_f32_e32 v78, v78, v96
	v_sub_f32_e32 v77, v77, v96
	v_sub_f32_e32 v76, v76, v96
	v_sub_f32_e32 v75, v75, v96
	v_sub_f32_e32 v74, v74, v96
	v_sub_f32_e32 v73, v73, v96
	v_sub_f32_e32 v72, v72, v96
	v_sub_f32_e32 v71, v71, v96
	v_sub_f32_e32 v70, v70, v96
	v_sub_f32_e32 v69, v69, v96
	v_sub_f32_e32 v68, v68, v96
	v_sub_f32_e32 v67, v67, v96
	v_sub_f32_e32 v66, v66, v96
	v_sub_f32_e32 v65, v65, v96
	v_sub_f32_e32 v64, v64, v96
	v_sub_f32_e32 v95, v95, v96
	v_sub_f32_e32 v94, v94, v96
	v_sub_f32_e32 v93, v93, v96
	v_sub_f32_e32 v92, v92, v96
	v_sub_f32_e32 v91, v91, v96
	v_sub_f32_e32 v90, v90, v96
	v_sub_f32_e32 v89, v89, v96
	v_sub_f32_e32 v88, v88, v96
	v_sub_f32_e32 v87, v87, v96
	v_sub_f32_e32 v86, v86, v96
	v_sub_f32_e32 v85, v85, v96
	v_sub_f32_e32 v84, v84, v96
	v_sub_f32_e32 v83, v83, v96
	v_sub_f32_e32 v82, v82, v96
	v_sub_f32_e32 v81, v81, v96
	v_sub_f32_e32 v80, v80, v96
